# attention loop: common path made fall-through (causal-mask block and last-tile drain out of line, one counted wait for all waves): two fewer taken branches per half
# baseline (speedup 1.0000x reference)
; #define WAIT_BAR(N) asm volatile("s_waitcnt vmcnt(" #N ") lgkmcnt(0)\n\ts_barrier" ::: "memory")
; __device__ __forceinline__ void attn_unit(int b, int h, int qb, const bf16* Q, const bf16* __restrict__ Kn, const bf16* __restrict__ Kpe, const bf16* __restrict__ V, bf16* O, float* ASS, LAS char* shm) {
;     ...
;         for (int t = 0; t < NT; ++t) {
;             if (t + 1 < NT) { WAIT_BAR(3); } else { WAIT_BAR(0); }
;     ...
;         for (int t = 0; t < NT; ++t) {
;             if (t + 1 < NT) { WAIT_BAR(3); } else { WAIT_BAR(0); }
.Lat_u1_loop:
	s_add_i32 s4, s52, 1
	s_cmp_ge_u32 s4, s86
	s_cbranch_scc1 .Lat_u1x_lw
	s_waitcnt vmcnt(2) lgkmcnt(0)

.Lat_u1x_nodma:
	v_lshl_add_u64 v[126:127], v[126:127], 0, s[34:35]
	v_lshl_add_u64 v[14:15], v[14:15], 0, s[20:21]
	v_lshl_add_u64 v[124:125], v[124:125], 0, s[34:35]
	v_add_f32_e32 v157, v157, v58
	v_add_f32_e32 v157, v157, v59
	v_cvt_pk_bf16_f32 v53, v58, v59
	v_exp_f32_e32 v60, v60
	v_exp_f32_e32 v61, v61
	v_mfma_f32_32x32x16_bf16 v[16:31], v[200:203], v[68:71], v[16:31]
	v_add_f32_e32 v156, v156, v60
	v_add_f32_e32 v156, v156, v61
	v_cvt_pk_bf16_f32 v54, v60, v61
	v_exp_f32_e32 v62, v62
	v_exp_f32_e32 v63, v63
	v_mfma_f32_32x32x16_bf16 v[32:47], v[230:233], v[68:71], v[32:47]
	v_add_f32_e32 v157, v157, v62
	v_add_f32_e32 v157, v157, v63
	v_cvt_pk_bf16_f32 v55, v62, v63
	s_nop 1
	v_mfma_f32_32x32x16_bf16 v[16:31], v[204:207], v[48:51], v[16:31]
	v_mfma_f32_32x32x16_bf16 v[32:47], v[234:237], v[48:51], v[32:47]
	v_mfma_f32_32x32x16_bf16 v[16:31], v[208:211], v[52:55], v[16:31]
	v_mfma_f32_32x32x16_bf16 v[32:47], v[164:167], v[52:55], v[32:47]
	v_add_f32_e32 v156, v156, v157
	v_add_f32_e32 v128, v128, v156
	s_cmp_lt_u32 s52, s87
	s_cbranch_scc0 .Lat_u1x_mk

; #define WAIT_BAR(N) asm volatile("s_waitcnt vmcnt(" #N ") lgkmcnt(0)\n\ts_barrier" ::: "memory")
; __device__ __forceinline__ void attn_unit(int b, int h, int qb, const bf16* Q, const bf16* __restrict__ Kn, const bf16* __restrict__ Kpe, const bf16* __restrict__ V, bf16* O, float* ASS, LAS char* shm) {
;     ...
;         for (int t = 0; t < NT; ++t) {
;             if (t + 1 < NT) { WAIT_BAR(3); } else { WAIT_BAR(0); }
;     ...
;         for (int t = 0; t < NT; ++t) {
;             if (t + 1 < NT) { WAIT_BAR(3); } else { WAIT_BAR(0); }
.Lat_u1x_end:
	s_cmp_eq_u32 s52, s86
	s_cbranch_scc1 .Lat_u1_tail
	s_add_i32 s4, s52, 1
	s_cmp_ge_u32 s4, s86
	s_cbranch_scc1 .Lat_u1y_lw
	s_waitcnt vmcnt(2) lgkmcnt(0)

.Lat_u1y_nodma:
	v_lshl_add_u64 v[126:127], v[126:127], 0, s[34:35]
	v_lshl_add_u64 v[14:15], v[14:15], 0, s[20:21]
	v_lshl_add_u64 v[124:125], v[124:125], 0, s[34:35]
	v_add_f32_e32 v157, v157, v190
	v_add_f32_e32 v157, v157, v191
	v_cvt_pk_bf16_f32 v185, v190, v191
	v_exp_f32_e32 v192, v192
	v_exp_f32_e32 v193, v193
	v_mfma_f32_32x32x16_bf16 v[16:31], v[200:203], v[242:245], v[16:31]
	v_add_f32_e32 v156, v156, v192
	v_add_f32_e32 v156, v156, v193
	v_cvt_pk_bf16_f32 v186, v192, v193
	v_exp_f32_e32 v194, v194
	v_exp_f32_e32 v195, v195
	v_mfma_f32_32x32x16_bf16 v[32:47], v[230:233], v[242:245], v[32:47]
	v_add_f32_e32 v157, v157, v194
	v_add_f32_e32 v157, v157, v195
	v_cvt_pk_bf16_f32 v187, v194, v195
	s_nop 1
	v_mfma_f32_32x32x16_bf16 v[16:31], v[204:207], v[180:183], v[16:31]
	v_mfma_f32_32x32x16_bf16 v[32:47], v[234:237], v[180:183], v[32:47]
	v_mfma_f32_32x32x16_bf16 v[16:31], v[208:211], v[184:187], v[16:31]
	v_mfma_f32_32x32x16_bf16 v[32:47], v[164:167], v[184:187], v[32:47]
	v_add_f32_e32 v156, v156, v157
	v_add_f32_e32 v128, v128, v156
	s_cmp_lt_u32 s52, s87
	s_cbranch_scc0 .Lat_u1y_mk

; __device__ __forceinline__ void cmask(f32x16& p0, f32x16& p1, int jb, int qrel, int hi) {
;     const float NEG = -INFINITY; const int kb = 64 * jb + 4 * hi;
; #pragma unroll
;     for (int r = 0; r < 16; ++r) { const int kv = kb + (r & 3) + 8 * (r >> 2); if (kv > qrel) p0[r] = NEG; if (kv + 32 > qrel) p1[r] = NEG; }
; }
.Lat_u1x_mk:
	s_sub_i32 s4, s52, s87
	s_lshl_b32 s4, s4, 6
	s_nop 7
	s_nop 7
	v_lshl_add_u32 v147, v141, 2, s4
	v_sub_u32_e32 v147, v145, v147
	s_nop 0
	v_cmp_gt_i32_e32 vcc, 0, v147
	v_cmp_gt_i32_e64 s[4:5], 1, v147
	v_cmp_gt_i32_e64 s[46:47], 2, v147
	v_cndmask_b32_e32 v238, v238, v220, vcc
	v_cmp_gt_i32_e32 vcc, 3, v147
	v_cndmask_b32_e64 v239, v239, v220, s[4:5]
	v_cmp_gt_i32_e64 s[4:5], 8, v147
	v_cndmask_b32_e64 v240, v240, v220, s[46:47]
	v_cmp_gt_i32_e64 s[46:47], 9, v147
	v_cndmask_b32_e32 v241, v241, v220, vcc
	v_cmp_gt_i32_e32 vcc, 10, v147
	v_cndmask_b32_e64 v242, v242, v220, s[4:5]
	v_cmp_gt_i32_e64 s[4:5], 11, v147
	v_cndmask_b32_e64 v243, v243, v220, s[46:47]
	v_cmp_gt_i32_e64 s[46:47], 16, v147
	v_cndmask_b32_e32 v244, v244, v220, vcc
	v_cmp_gt_i32_e32 vcc, 17, v147
	v_cndmask_b32_e64 v245, v245, v220, s[4:5]
	v_cmp_gt_i32_e64 s[4:5], 18, v147
	v_cndmask_b32_e64 v246, v246, v220, s[46:47]
	v_cmp_gt_i32_e64 s[46:47], 19, v147
	v_cndmask_b32_e32 v247, v247, v220, vcc
	v_cmp_gt_i32_e32 vcc, 24, v147
	v_cndmask_b32_e64 v248, v248, v220, s[4:5]
	v_cmp_gt_i32_e64 s[4:5], 25, v147
	v_cndmask_b32_e64 v249, v249, v220, s[46:47]
	v_cmp_gt_i32_e64 s[46:47], 26, v147
	v_cndmask_b32_e32 v250, v250, v220, vcc
	v_cmp_gt_i32_e32 vcc, 27, v147
	v_cndmask_b32_e64 v251, v251, v220, s[4:5]
	v_cmp_gt_i32_e64 s[4:5], 32, v147
	v_cndmask_b32_e64 v252, v252, v220, s[46:47]
	v_cmp_gt_i32_e64 s[46:47], 33, v147
	v_cndmask_b32_e32 v253, v253, v220, vcc
	v_cmp_gt_i32_e32 vcc, 34, v147
	v_cndmask_b32_e64 v180, v180, v220, s[4:5]
	v_cmp_gt_i32_e64 s[4:5], 35, v147
	v_cndmask_b32_e64 v181, v181, v220, s[46:47]
	v_cmp_gt_i32_e64 s[46:47], 40, v147
	v_cndmask_b32_e32 v182, v182, v220, vcc
	v_cmp_gt_i32_e32 vcc, 41, v147
	v_cndmask_b32_e64 v183, v183, v220, s[4:5]
	v_cmp_gt_i32_e64 s[4:5], 42, v147
	v_cndmask_b32_e64 v184, v184, v220, s[46:47]
	v_cmp_gt_i32_e64 s[46:47], 43, v147
	v_cndmask_b32_e32 v185, v185, v220, vcc
	v_cmp_gt_i32_e32 vcc, 48, v147
	v_cndmask_b32_e64 v186, v186, v220, s[4:5]
	v_cmp_gt_i32_e64 s[4:5], 49, v147
	v_cndmask_b32_e64 v187, v187, v220, s[46:47]
	v_cmp_gt_i32_e64 s[46:47], 50, v147
	v_cndmask_b32_e32 v188, v188, v220, vcc
	v_cmp_gt_i32_e32 vcc, 51, v147
	v_cndmask_b32_e64 v189, v189, v220, s[4:5]
	v_cmp_gt_i32_e64 s[4:5], 56, v147
	v_cndmask_b32_e64 v190, v190, v220, s[46:47]
	v_cmp_gt_i32_e64 s[46:47], 57, v147
	v_cndmask_b32_e32 v191, v191, v220, vcc
	v_cmp_gt_i32_e32 vcc, 58, v147
	v_cndmask_b32_e64 v192, v192, v220, s[4:5]
	v_cmp_gt_i32_e64 s[4:5], 59, v147
	v_cndmask_b32_e64 v193, v193, v220, s[46:47]
	v_cndmask_b32_e32 v194, v194, v220, vcc
	v_cndmask_b32_e64 v195, v195, v220, s[4:5]
	s_branch .Lat_u1x_nomask
.Lat_u1y_mk:
	s_sub_i32 s4, s52, s87
	s_lshl_b32 s4, s4, 6
	s_nop 7
	s_nop 7
	v_lshl_add_u32 v147, v141, 2, s4
	v_sub_u32_e32 v147, v145, v147
	s_nop 0
	v_cmp_gt_i32_e32 vcc, 0, v147
	v_cmp_gt_i32_e64 s[4:5], 1, v147
	v_cmp_gt_i32_e64 s[46:47], 2, v147
	v_cndmask_b32_e32 v64, v64, v220, vcc
	v_cmp_gt_i32_e32 vcc, 3, v147
	v_cndmask_b32_e64 v65, v65, v220, s[4:5]
	v_cmp_gt_i32_e64 s[4:5], 8, v147
	v_cndmask_b32_e64 v66, v66, v220, s[46:47]
	v_cmp_gt_i32_e64 s[46:47], 9, v147
	v_cndmask_b32_e32 v67, v67, v220, vcc
	v_cmp_gt_i32_e32 vcc, 10, v147
	v_cndmask_b32_e64 v68, v68, v220, s[4:5]
	v_cmp_gt_i32_e64 s[4:5], 11, v147
	v_cndmask_b32_e64 v69, v69, v220, s[46:47]
	v_cmp_gt_i32_e64 s[46:47], 16, v147
	v_cndmask_b32_e32 v70, v70, v220, vcc
	v_cmp_gt_i32_e32 vcc, 17, v147
	v_cndmask_b32_e64 v71, v71, v220, s[4:5]
	v_cmp_gt_i32_e64 s[4:5], 18, v147
	v_cndmask_b32_e64 v72, v72, v220, s[46:47]
	v_cmp_gt_i32_e64 s[46:47], 19, v147
	v_cndmask_b32_e32 v73, v73, v220, vcc
	v_cmp_gt_i32_e32 vcc, 24, v147
	v_cndmask_b32_e64 v74, v74, v220, s[4:5]
	v_cmp_gt_i32_e64 s[4:5], 25, v147
	v_cndmask_b32_e64 v75, v75, v220, s[46:47]
	v_cmp_gt_i32_e64 s[46:47], 26, v147
	v_cndmask_b32_e32 v76, v76, v220, vcc
	v_cmp_gt_i32_e32 vcc, 27, v147
	v_cndmask_b32_e64 v77, v77, v220, s[4:5]
	v_cmp_gt_i32_e64 s[4:5], 32, v147
	v_cndmask_b32_e64 v78, v78, v220, s[46:47]
	v_cmp_gt_i32_e64 s[46:47], 33, v147
	v_cndmask_b32_e32 v79, v79, v220, vcc
	v_cmp_gt_i32_e32 vcc, 34, v147
	v_cndmask_b32_e64 v48, v48, v220, s[4:5]
	v_cmp_gt_i32_e64 s[4:5], 35, v147
	v_cndmask_b32_e64 v49, v49, v220, s[46:47]
	v_cmp_gt_i32_e64 s[46:47], 40, v147
	v_cndmask_b32_e32 v50, v50, v220, vcc
	v_cmp_gt_i32_e32 vcc, 41, v147
	v_cndmask_b32_e64 v51, v51, v220, s[4:5]
	v_cmp_gt_i32_e64 s[4:5], 42, v147
	v_cndmask_b32_e64 v52, v52, v220, s[46:47]
	v_cmp_gt_i32_e64 s[46:47], 43, v147
	v_cndmask_b32_e32 v53, v53, v220, vcc
	v_cmp_gt_i32_e32 vcc, 48, v147
	v_cndmask_b32_e64 v54, v54, v220, s[4:5]
	v_cmp_gt_i32_e64 s[4:5], 49, v147
	v_cndmask_b32_e64 v55, v55, v220, s[46:47]
	v_cmp_gt_i32_e64 s[46:47], 50, v147
	v_cndmask_b32_e32 v56, v56, v220, vcc
	v_cmp_gt_i32_e32 vcc, 51, v147
	v_cndmask_b32_e64 v57, v57, v220, s[4:5]
	v_cmp_gt_i32_e64 s[4:5], 56, v147
	v_cndmask_b32_e64 v58, v58, v220, s[46:47]
	v_cmp_gt_i32_e64 s[46:47], 57, v147
	v_cndmask_b32_e32 v59, v59, v220, vcc
	v_cmp_gt_i32_e32 vcc, 58, v147
	v_cndmask_b32_e64 v60, v60, v220, s[4:5]
	v_cmp_gt_i32_e64 s[4:5], 59, v147
	v_cndmask_b32_e64 v61, v61, v220, s[46:47]
	v_cndmask_b32_e32 v62, v62, v220, vcc
	v_cndmask_b32_e64 v63, v63, v220, s[4:5]
	s_branch .Lat_u1y_nomask
.Lat_u1x_lw:
	s_waitcnt vmcnt(0) lgkmcnt(0)
	s_branch .Lat_u1x_bar

; #define WAIT_BAR(N) asm volatile("s_waitcnt vmcnt(" #N ") lgkmcnt(0)\n\ts_barrier" ::: "memory")
; __device__ __forceinline__ void attn_unit(int b, int h, int qb, const bf16* Q, const bf16* __restrict__ Kn, const bf16* __restrict__ Kpe, const bf16* __restrict__ V, bf16* O, float* ASS, LAS char* shm) {
;     ...
;         for (int t = 0; t < NT; ++t) {
;             if (t + 1 < NT) { WAIT_BAR(3); } else { WAIT_BAR(0); }
;     ...
;         for (int t = 0; t < NT; ++t) {
;             if (t + 1 < NT) { WAIT_BAR(3); } else { WAIT_BAR(0); }
.Lat_u2_loop:
	s_add_i32 s4, s62, 1
	s_cmp_ge_u32 s4, s90
	s_cbranch_scc1 .Lat_u2x_lw
	s_waitcnt vmcnt(2) lgkmcnt(0)

.Lat_u2x_nodma:
	v_lshl_add_u64 v[126:127], v[126:127], 0, s[34:35]
	v_lshl_add_u64 v[122:123], v[122:123], 0, s[20:21]
	v_lshl_add_u64 v[124:125], v[124:125], 0, s[34:35]
	v_add_f32_e32 v157, v157, v44
	v_add_f32_e32 v157, v157, v45
	v_cvt_pk_bf16_f32 v39, v44, v45
	v_exp_f32_e32 v46, v46
	v_exp_f32_e32 v47, v47
	v_mfma_f32_32x32x16_bf16 v[18:33], v[200:203], v[54:57], v[18:33]
	v_add_f32_e32 v156, v156, v46
	v_add_f32_e32 v156, v156, v47
	v_cvt_pk_bf16_f32 v40, v46, v47
	v_exp_f32_e32 v48, v48
	v_exp_f32_e32 v49, v49
	v_mfma_f32_32x32x16_bf16 v[2:17], v[230:233], v[54:57], v[2:17]
	v_add_f32_e32 v157, v157, v48
	v_add_f32_e32 v157, v157, v49
	v_cvt_pk_bf16_f32 v41, v48, v49
	s_nop 1
	v_mfma_f32_32x32x16_bf16 v[18:33], v[204:207], v[34:37], v[18:33]
	v_mfma_f32_32x32x16_bf16 v[2:17], v[234:237], v[34:37], v[2:17]
	v_mfma_f32_32x32x16_bf16 v[18:33], v[208:211], v[38:41], v[18:33]
	v_mfma_f32_32x32x16_bf16 v[2:17], v[164:167], v[38:41], v[2:17]
	v_add_f32_e32 v156, v156, v157
	v_add_f32_e32 v128, v128, v156
	s_cmp_lt_u32 s62, s91
	s_cbranch_scc0 .Lat_u2x_mk

; #define WAIT_BAR(N) asm volatile("s_waitcnt vmcnt(" #N ") lgkmcnt(0)\n\ts_barrier" ::: "memory")
; __device__ __forceinline__ void attn_unit(int b, int h, int qb, const bf16* Q, const bf16* __restrict__ Kn, const bf16* __restrict__ Kpe, const bf16* __restrict__ V, bf16* O, float* ASS, LAS char* shm) {
;     ...
;         for (int t = 0; t < NT; ++t) {
;             if (t + 1 < NT) { WAIT_BAR(3); } else { WAIT_BAR(0); }
;     ...
;         for (int t = 0; t < NT; ++t) {
;             if (t + 1 < NT) { WAIT_BAR(3); } else { WAIT_BAR(0); }
.Lat_u2x_end:
	s_cmp_eq_u32 s62, s90
	s_cbranch_scc1 .Lat_u2_tail
	s_add_i32 s4, s62, 1
	s_cmp_ge_u32 s4, s90
	s_cbranch_scc1 .Lat_u2y_lw
	s_waitcnt vmcnt(2) lgkmcnt(0)

.Lat_u2y_nodma:
	v_lshl_add_u64 v[126:127], v[126:127], 0, s[34:35]
	v_lshl_add_u64 v[122:123], v[122:123], 0, s[20:21]
	v_lshl_add_u64 v[124:125], v[124:125], 0, s[34:35]
	v_add_f32_e32 v157, v157, v190
	v_add_f32_e32 v157, v157, v191
	v_cvt_pk_bf16_f32 v185, v190, v191
	v_exp_f32_e32 v192, v192
	v_exp_f32_e32 v193, v193
	v_mfma_f32_32x32x16_bf16 v[18:33], v[200:203], v[242:245], v[18:33]
	v_add_f32_e32 v156, v156, v192
	v_add_f32_e32 v156, v156, v193
	v_cvt_pk_bf16_f32 v186, v192, v193
	v_exp_f32_e32 v194, v194
	v_exp_f32_e32 v195, v195
	v_mfma_f32_32x32x16_bf16 v[2:17], v[230:233], v[242:245], v[2:17]
	v_add_f32_e32 v157, v157, v194
	v_add_f32_e32 v157, v157, v195
	v_cvt_pk_bf16_f32 v187, v194, v195
	s_nop 1
	v_mfma_f32_32x32x16_bf16 v[18:33], v[204:207], v[180:183], v[18:33]
	v_mfma_f32_32x32x16_bf16 v[2:17], v[234:237], v[180:183], v[2:17]
	v_mfma_f32_32x32x16_bf16 v[18:33], v[208:211], v[184:187], v[18:33]
	v_mfma_f32_32x32x16_bf16 v[2:17], v[164:167], v[184:187], v[2:17]
	v_add_f32_e32 v156, v156, v157
	v_add_f32_e32 v128, v128, v156
	s_cmp_lt_u32 s62, s91
	s_cbranch_scc0 .Lat_u2y_mk

; __device__ __forceinline__ void cmask(f32x16& p0, f32x16& p1, int jb, int qrel, int hi) {
;     const float NEG = -INFINITY; const int kb = 64 * jb + 4 * hi;
; #pragma unroll
;     for (int r = 0; r < 16; ++r) { const int kv = kb + (r & 3) + 8 * (r >> 2); if (kv > qrel) p0[r] = NEG; if (kv + 32 > qrel) p1[r] = NEG; }
; }
.Lat_u2x_mk:
	s_sub_i32 s4, s62, s91
	s_lshl_b32 s4, s4, 6
	s_nop 7
	s_nop 7
	v_lshl_add_u32 v133, v142, 2, s4
	v_sub_u32_e32 v133, v145, v133
	s_nop 0
	v_cmp_gt_i32_e32 vcc, 0, v133
	v_cmp_gt_i32_e64 s[4:5], 1, v133
	v_cmp_gt_i32_e64 s[54:55], 2, v133
	v_cndmask_b32_e32 v238, v238, v220, vcc
	v_cmp_gt_i32_e32 vcc, 3, v133
	v_cndmask_b32_e64 v239, v239, v220, s[4:5]
	v_cmp_gt_i32_e64 s[4:5], 8, v133
	v_cndmask_b32_e64 v240, v240, v220, s[54:55]
	v_cmp_gt_i32_e64 s[54:55], 9, v133
	v_cndmask_b32_e32 v241, v241, v220, vcc
	v_cmp_gt_i32_e32 vcc, 10, v133
	v_cndmask_b32_e64 v242, v242, v220, s[4:5]
	v_cmp_gt_i32_e64 s[4:5], 11, v133
	v_cndmask_b32_e64 v243, v243, v220, s[54:55]
	v_cmp_gt_i32_e64 s[54:55], 16, v133
	v_cndmask_b32_e32 v244, v244, v220, vcc
	v_cmp_gt_i32_e32 vcc, 17, v133
	v_cndmask_b32_e64 v245, v245, v220, s[4:5]
	v_cmp_gt_i32_e64 s[4:5], 18, v133
	v_cndmask_b32_e64 v246, v246, v220, s[54:55]
	v_cmp_gt_i32_e64 s[54:55], 19, v133
	v_cndmask_b32_e32 v247, v247, v220, vcc
	v_cmp_gt_i32_e32 vcc, 24, v133
	v_cndmask_b32_e64 v248, v248, v220, s[4:5]
	v_cmp_gt_i32_e64 s[4:5], 25, v133
	v_cndmask_b32_e64 v249, v249, v220, s[54:55]
	v_cmp_gt_i32_e64 s[54:55], 26, v133
	v_cndmask_b32_e32 v250, v250, v220, vcc
	v_cmp_gt_i32_e32 vcc, 27, v133
	v_cndmask_b32_e64 v251, v251, v220, s[4:5]
	v_cmp_gt_i32_e64 s[4:5], 32, v133
	v_cndmask_b32_e64 v252, v252, v220, s[54:55]
	v_cmp_gt_i32_e64 s[54:55], 33, v133
	v_cndmask_b32_e32 v253, v253, v220, vcc
	v_cmp_gt_i32_e32 vcc, 34, v133
	v_cndmask_b32_e64 v180, v180, v220, s[4:5]
	v_cmp_gt_i32_e64 s[4:5], 35, v133
	v_cndmask_b32_e64 v181, v181, v220, s[54:55]
	v_cmp_gt_i32_e64 s[54:55], 40, v133
	v_cndmask_b32_e32 v182, v182, v220, vcc
	v_cmp_gt_i32_e32 vcc, 41, v133
	v_cndmask_b32_e64 v183, v183, v220, s[4:5]
	v_cmp_gt_i32_e64 s[4:5], 42, v133
	v_cndmask_b32_e64 v184, v184, v220, s[54:55]
	v_cmp_gt_i32_e64 s[54:55], 43, v133
	v_cndmask_b32_e32 v185, v185, v220, vcc
	v_cmp_gt_i32_e32 vcc, 48, v133
	v_cndmask_b32_e64 v186, v186, v220, s[4:5]
	v_cmp_gt_i32_e64 s[4:5], 49, v133
	v_cndmask_b32_e64 v187, v187, v220, s[54:55]
	v_cmp_gt_i32_e64 s[54:55], 50, v133
	v_cndmask_b32_e32 v188, v188, v220, vcc
	v_cmp_gt_i32_e32 vcc, 51, v133
	v_cndmask_b32_e64 v189, v189, v220, s[4:5]
	v_cmp_gt_i32_e64 s[4:5], 56, v133
	v_cndmask_b32_e64 v190, v190, v220, s[54:55]
	v_cmp_gt_i32_e64 s[54:55], 57, v133
	v_cndmask_b32_e32 v191, v191, v220, vcc
	v_cmp_gt_i32_e32 vcc, 58, v133
	v_cndmask_b32_e64 v192, v192, v220, s[4:5]
	v_cmp_gt_i32_e64 s[4:5], 59, v133
	v_cndmask_b32_e64 v193, v193, v220, s[54:55]
	v_cndmask_b32_e32 v194, v194, v220, vcc
	v_cndmask_b32_e64 v195, v195, v220, s[4:5]
	s_branch .Lat_u2x_nomask
.Lat_u2y_mk:
	s_sub_i32 s4, s62, s91
	s_lshl_b32 s4, s4, 6
	s_nop 7
	s_nop 7
	v_lshl_add_u32 v133, v142, 2, s4
	v_sub_u32_e32 v133, v145, v133
	s_nop 0
	v_cmp_gt_i32_e32 vcc, 0, v133
	v_cmp_gt_i32_e64 s[4:5], 1, v133
	v_cmp_gt_i32_e64 s[54:55], 2, v133
	v_cndmask_b32_e32 v50, v50, v220, vcc
	v_cmp_gt_i32_e32 vcc, 3, v133
	v_cndmask_b32_e64 v51, v51, v220, s[4:5]
	v_cmp_gt_i32_e64 s[4:5], 8, v133
	v_cndmask_b32_e64 v52, v52, v220, s[54:55]
	v_cmp_gt_i32_e64 s[54:55], 9, v133
	v_cndmask_b32_e32 v53, v53, v220, vcc
	v_cmp_gt_i32_e32 vcc, 10, v133
	v_cndmask_b32_e64 v54, v54, v220, s[4:5]
	v_cmp_gt_i32_e64 s[4:5], 11, v133
	v_cndmask_b32_e64 v55, v55, v220, s[54:55]
	v_cmp_gt_i32_e64 s[54:55], 16, v133
	v_cndmask_b32_e32 v56, v56, v220, vcc
	v_cmp_gt_i32_e32 vcc, 17, v133
	v_cndmask_b32_e64 v57, v57, v220, s[4:5]
	v_cmp_gt_i32_e64 s[4:5], 18, v133
	v_cndmask_b32_e64 v58, v58, v220, s[54:55]
	v_cmp_gt_i32_e64 s[54:55], 19, v133
	v_cndmask_b32_e32 v59, v59, v220, vcc
	v_cmp_gt_i32_e32 vcc, 24, v133
	v_cndmask_b32_e64 v60, v60, v220, s[4:5]
	v_cmp_gt_i32_e64 s[4:5], 25, v133
	v_cndmask_b32_e64 v61, v61, v220, s[54:55]
	v_cmp_gt_i32_e64 s[54:55], 26, v133
	v_cndmask_b32_e32 v62, v62, v220, vcc
	v_cmp_gt_i32_e32 vcc, 27, v133
	v_cndmask_b32_e64 v63, v63, v220, s[4:5]
	v_cmp_gt_i32_e64 s[4:5], 32, v133
	v_cndmask_b32_e64 v64, v64, v220, s[54:55]
	v_cmp_gt_i32_e64 s[54:55], 33, v133
	v_cndmask_b32_e32 v65, v65, v220, vcc
	v_cmp_gt_i32_e32 vcc, 34, v133
	v_cndmask_b32_e64 v34, v34, v220, s[4:5]
	v_cmp_gt_i32_e64 s[4:5], 35, v133
	v_cndmask_b32_e64 v35, v35, v220, s[54:55]
	v_cmp_gt_i32_e64 s[54:55], 40, v133
	v_cndmask_b32_e32 v36, v36, v220, vcc
	v_cmp_gt_i32_e32 vcc, 41, v133
	v_cndmask_b32_e64 v37, v37, v220, s[4:5]
	v_cmp_gt_i32_e64 s[4:5], 42, v133
	v_cndmask_b32_e64 v38, v38, v220, s[54:55]
	v_cmp_gt_i32_e64 s[54:55], 43, v133
	v_cndmask_b32_e32 v39, v39, v220, vcc
	v_cmp_gt_i32_e32 vcc, 48, v133
	v_cndmask_b32_e64 v40, v40, v220, s[4:5]
	v_cmp_gt_i32_e64 s[4:5], 49, v133
	v_cndmask_b32_e64 v41, v41, v220, s[54:55]
	v_cmp_gt_i32_e64 s[54:55], 50, v133
	v_cndmask_b32_e32 v42, v42, v220, vcc
	v_cmp_gt_i32_e32 vcc, 51, v133
	v_cndmask_b32_e64 v43, v43, v220, s[4:5]
	v_cmp_gt_i32_e64 s[4:5], 56, v133
	v_cndmask_b32_e64 v44, v44, v220, s[54:55]
	v_cmp_gt_i32_e64 s[54:55], 57, v133
	v_cndmask_b32_e32 v45, v45, v220, vcc
	v_cmp_gt_i32_e32 vcc, 58, v133
	v_cndmask_b32_e64 v46, v46, v220, s[4:5]
	v_cmp_gt_i32_e64 s[4:5], 59, v133
	v_cndmask_b32_e64 v47, v47, v220, s[54:55]
	v_cndmask_b32_e32 v48, v48, v220, vcc
	v_cndmask_b32_e64 v49, v49, v220, s[4:5]
	s_branch .Lat_u2y_nomask
